# top-k threshold search starts from a verified bracket below the row max (interval bisection, about 12 counting passes instead of 18)
# speedup vs baseline: 1.0025x; 1.0015x over previous
.Ltk0_cn31:
.Ltk0_cvd:
.Ltk0_binit:
	v_mov_b32_e32 v160, 0
	v_mov_b32_e32 v161, 0
	v_max3_u32 v160, v160, v32, v33
	v_max3_u32 v161, v161, v34, v35
	v_max3_u32 v160, v160, v36, v37
	v_max3_u32 v161, v161, v38, v39
	s_cmp_le_u32 s23, 2
	s_cbranch_scc1 .Ltk0_mxd
	v_max3_u32 v160, v160, v40, v41
	v_max3_u32 v161, v161, v42, v43
	v_max3_u32 v160, v160, v44, v45
	v_max3_u32 v161, v161, v46, v47
	s_cmp_le_u32 s23, 4
	s_cbranch_scc1 .Ltk0_mxd
	v_max3_u32 v160, v160, v48, v49
	v_max3_u32 v161, v161, v50, v51
	v_max3_u32 v160, v160, v52, v53
	v_max3_u32 v161, v161, v54, v55
	s_cmp_le_u32 s23, 6
	s_cbranch_scc1 .Ltk0_mxd
	v_max3_u32 v160, v160, v56, v57
	v_max3_u32 v161, v161, v58, v59
	v_max3_u32 v160, v160, v60, v61
	v_max3_u32 v161, v161, v62, v63
	s_cmp_le_u32 s23, 8
	s_cbranch_scc1 .Ltk0_mxd
	v_max3_u32 v160, v160, v64, v65
	v_max3_u32 v161, v161, v66, v67
	v_max3_u32 v160, v160, v68, v69
	v_max3_u32 v161, v161, v70, v71
	s_cmp_le_u32 s23, 10
	s_cbranch_scc1 .Ltk0_mxd
	v_max3_u32 v160, v160, v72, v73
	v_max3_u32 v161, v161, v74, v75
	v_max3_u32 v160, v160, v76, v77
	v_max3_u32 v161, v161, v78, v79
	s_cmp_le_u32 s23, 12
	s_cbranch_scc1 .Ltk0_mxd
	v_max3_u32 v160, v160, v80, v81
	v_max3_u32 v161, v161, v82, v83
	v_max3_u32 v160, v160, v84, v85
	v_max3_u32 v161, v161, v86, v87
	s_cmp_le_u32 s23, 14
	s_cbranch_scc1 .Ltk0_mxd
	v_max3_u32 v160, v160, v88, v89
	v_max3_u32 v161, v161, v90, v91
	v_max3_u32 v160, v160, v92, v93
	v_max3_u32 v161, v161, v94, v95
	s_cmp_le_u32 s23, 16
	s_cbranch_scc1 .Ltk0_mxd
	v_max3_u32 v160, v160, v96, v97
	v_max3_u32 v161, v161, v98, v99
	v_max3_u32 v160, v160, v100, v101
	v_max3_u32 v161, v161, v102, v103
	s_cmp_le_u32 s23, 18
	s_cbranch_scc1 .Ltk0_mxd
	v_max3_u32 v160, v160, v104, v105
	v_max3_u32 v161, v161, v106, v107
	v_max3_u32 v160, v160, v108, v109
	v_max3_u32 v161, v161, v110, v111
	s_cmp_le_u32 s23, 20
	s_cbranch_scc1 .Ltk0_mxd
	v_max3_u32 v160, v160, v112, v113
	v_max3_u32 v161, v161, v114, v115
	v_max3_u32 v160, v160, v116, v117
	v_max3_u32 v161, v161, v118, v119
	s_cmp_le_u32 s23, 22
	s_cbranch_scc1 .Ltk0_mxd
	v_max3_u32 v160, v160, v120, v121
	v_max3_u32 v161, v161, v122, v123
	v_max3_u32 v160, v160, v124, v125
	v_max3_u32 v161, v161, v126, v127
	s_cmp_le_u32 s23, 24
	s_cbranch_scc1 .Ltk0_mxd
	v_max3_u32 v160, v160, v128, v129
	v_max3_u32 v161, v161, v130, v131
	v_max3_u32 v160, v160, v132, v133
	v_max3_u32 v161, v161, v134, v135
	s_cmp_le_u32 s23, 26
	s_cbranch_scc1 .Ltk0_mxd
	v_max3_u32 v160, v160, v136, v137
	v_max3_u32 v161, v161, v138, v139
	v_max3_u32 v160, v160, v140, v141
	v_max3_u32 v161, v161, v142, v143
	s_cmp_le_u32 s23, 28
	s_cbranch_scc1 .Ltk0_mxd
	v_max3_u32 v160, v160, v144, v145
	v_max3_u32 v161, v161, v146, v147
	v_max3_u32 v160, v160, v148, v149
	v_max3_u32 v161, v161, v150, v151
	s_cmp_le_u32 s23, 30
	s_cbranch_scc1 .Ltk0_mxd
	v_max3_u32 v160, v160, v152, v153
	v_max3_u32 v161, v161, v154, v155
	v_max3_u32 v160, v160, v156, v157
	v_max3_u32 v161, v161, v158, v159

.Ltk0_count:
	v_mov_b32_e32 v160, 0
	v_mov_b32_e32 v161, 0
	s_mov_b32 s22, 0
	v_cmp_le_u32_e64 s[34:35], s30, v32
	v_cmp_le_u32_e64 s[36:37], s30, v33
	v_cmp_le_u32_e64 s[48:49], s30, v34
	v_addc_co_u32_e64 v160, vcc, 0, v160, s[34:35]
	v_cmp_le_u32_e64 s[50:51], s30, v35
	v_addc_co_u32_e64 v161, vcc, 0, v161, s[36:37]
	v_cmp_le_u32_e64 s[34:35], s30, v36
	v_addc_co_u32_e64 v160, vcc, 0, v160, s[48:49]
	v_cmp_le_u32_e64 s[36:37], s30, v37
	v_addc_co_u32_e64 v161, vcc, 0, v161, s[50:51]
	v_cmp_le_u32_e64 s[48:49], s30, v38
	v_addc_co_u32_e64 v160, vcc, 0, v160, s[34:35]
	v_cmp_le_u32_e64 s[50:51], s30, v39
	v_addc_co_u32_e64 v161, vcc, 0, v161, s[36:37]
	v_addc_co_u32_e64 v160, vcc, 0, v160, s[48:49]
	v_addc_co_u32_e64 v161, vcc, 0, v161, s[50:51]
	s_cmp_le_u32 s23, 2
	s_cbranch_scc1 .Ltk0_bred
	v_cmp_le_u32_e64 s[34:35], s30, v40
	v_cmp_le_u32_e64 s[36:37], s30, v41
	v_cmp_le_u32_e64 s[48:49], s30, v42
	v_addc_co_u32_e64 v160, vcc, 0, v160, s[34:35]
	v_cmp_le_u32_e64 s[50:51], s30, v43
	v_addc_co_u32_e64 v161, vcc, 0, v161, s[36:37]
	v_cmp_le_u32_e64 s[34:35], s30, v44
	v_addc_co_u32_e64 v160, vcc, 0, v160, s[48:49]
	v_cmp_le_u32_e64 s[36:37], s30, v45
	v_addc_co_u32_e64 v161, vcc, 0, v161, s[50:51]
	v_cmp_le_u32_e64 s[48:49], s30, v46
	v_addc_co_u32_e64 v160, vcc, 0, v160, s[34:35]
	v_cmp_le_u32_e64 s[50:51], s30, v47
	v_addc_co_u32_e64 v161, vcc, 0, v161, s[36:37]
	v_addc_co_u32_e64 v160, vcc, 0, v160, s[48:49]
	v_addc_co_u32_e64 v161, vcc, 0, v161, s[50:51]
	s_cmp_le_u32 s23, 4
	s_cbranch_scc1 .Ltk0_bred
	v_cmp_le_u32_e64 s[34:35], s30, v48
	v_cmp_le_u32_e64 s[36:37], s30, v49
	v_cmp_le_u32_e64 s[48:49], s30, v50
	v_addc_co_u32_e64 v160, vcc, 0, v160, s[34:35]
	v_cmp_le_u32_e64 s[50:51], s30, v51
	v_addc_co_u32_e64 v161, vcc, 0, v161, s[36:37]
	v_cmp_le_u32_e64 s[34:35], s30, v52
	v_addc_co_u32_e64 v160, vcc, 0, v160, s[48:49]
	v_cmp_le_u32_e64 s[36:37], s30, v53
	v_addc_co_u32_e64 v161, vcc, 0, v161, s[50:51]
	v_cmp_le_u32_e64 s[48:49], s30, v54
	v_addc_co_u32_e64 v160, vcc, 0, v160, s[34:35]
	v_cmp_le_u32_e64 s[50:51], s30, v55
	v_addc_co_u32_e64 v161, vcc, 0, v161, s[36:37]
	v_addc_co_u32_e64 v160, vcc, 0, v160, s[48:49]
	v_addc_co_u32_e64 v161, vcc, 0, v161, s[50:51]
	s_cmp_le_u32 s23, 6
	s_cbranch_scc1 .Ltk0_bred
	v_cmp_le_u32_e64 s[34:35], s30, v56
	v_cmp_le_u32_e64 s[36:37], s30, v57
	v_cmp_le_u32_e64 s[48:49], s30, v58
	v_addc_co_u32_e64 v160, vcc, 0, v160, s[34:35]
	v_cmp_le_u32_e64 s[50:51], s30, v59
	v_addc_co_u32_e64 v161, vcc, 0, v161, s[36:37]
	v_cmp_le_u32_e64 s[34:35], s30, v60
	v_addc_co_u32_e64 v160, vcc, 0, v160, s[48:49]
	v_cmp_le_u32_e64 s[36:37], s30, v61
	v_addc_co_u32_e64 v161, vcc, 0, v161, s[50:51]
	v_cmp_le_u32_e64 s[48:49], s30, v62
	v_addc_co_u32_e64 v160, vcc, 0, v160, s[34:35]
	v_cmp_le_u32_e64 s[50:51], s30, v63
	v_addc_co_u32_e64 v161, vcc, 0, v161, s[36:37]
	v_addc_co_u32_e64 v160, vcc, 0, v160, s[48:49]
	v_addc_co_u32_e64 v161, vcc, 0, v161, s[50:51]
	s_cmp_le_u32 s23, 8
	s_cbranch_scc1 .Ltk0_bred
	v_cmp_le_u32_e64 s[34:35], s30, v64
	v_cmp_le_u32_e64 s[36:37], s30, v65
	v_cmp_le_u32_e64 s[48:49], s30, v66
	v_addc_co_u32_e64 v160, vcc, 0, v160, s[34:35]
	v_cmp_le_u32_e64 s[50:51], s30, v67
	v_addc_co_u32_e64 v161, vcc, 0, v161, s[36:37]
	v_cmp_le_u32_e64 s[34:35], s30, v68
	v_addc_co_u32_e64 v160, vcc, 0, v160, s[48:49]
	v_cmp_le_u32_e64 s[36:37], s30, v69
	v_addc_co_u32_e64 v161, vcc, 0, v161, s[50:51]
	v_cmp_le_u32_e64 s[48:49], s30, v70
	v_addc_co_u32_e64 v160, vcc, 0, v160, s[34:35]
	v_cmp_le_u32_e64 s[50:51], s30, v71
	v_addc_co_u32_e64 v161, vcc, 0, v161, s[36:37]
	v_addc_co_u32_e64 v160, vcc, 0, v160, s[48:49]
	v_addc_co_u32_e64 v161, vcc, 0, v161, s[50:51]
	s_cmp_le_u32 s23, 10
	s_cbranch_scc1 .Ltk0_bred
	v_cmp_le_u32_e64 s[34:35], s30, v72
	v_cmp_le_u32_e64 s[36:37], s30, v73
	v_cmp_le_u32_e64 s[48:49], s30, v74
	v_addc_co_u32_e64 v160, vcc, 0, v160, s[34:35]
	v_cmp_le_u32_e64 s[50:51], s30, v75
	v_addc_co_u32_e64 v161, vcc, 0, v161, s[36:37]
	v_cmp_le_u32_e64 s[34:35], s30, v76
	v_addc_co_u32_e64 v160, vcc, 0, v160, s[48:49]
	v_cmp_le_u32_e64 s[36:37], s30, v77
	v_addc_co_u32_e64 v161, vcc, 0, v161, s[50:51]
	v_cmp_le_u32_e64 s[48:49], s30, v78
	v_addc_co_u32_e64 v160, vcc, 0, v160, s[34:35]
	v_cmp_le_u32_e64 s[50:51], s30, v79
	v_addc_co_u32_e64 v161, vcc, 0, v161, s[36:37]
	v_addc_co_u32_e64 v160, vcc, 0, v160, s[48:49]
	v_addc_co_u32_e64 v161, vcc, 0, v161, s[50:51]
	s_cmp_le_u32 s23, 12
	s_cbranch_scc1 .Ltk0_bred
	v_cmp_le_u32_e64 s[34:35], s30, v80
	v_cmp_le_u32_e64 s[36:37], s30, v81
	v_cmp_le_u32_e64 s[48:49], s30, v82
	v_addc_co_u32_e64 v160, vcc, 0, v160, s[34:35]
	v_cmp_le_u32_e64 s[50:51], s30, v83
	v_addc_co_u32_e64 v161, vcc, 0, v161, s[36:37]
	v_cmp_le_u32_e64 s[34:35], s30, v84
	v_addc_co_u32_e64 v160, vcc, 0, v160, s[48:49]
	v_cmp_le_u32_e64 s[36:37], s30, v85
	v_addc_co_u32_e64 v161, vcc, 0, v161, s[50:51]
	v_cmp_le_u32_e64 s[48:49], s30, v86
	v_addc_co_u32_e64 v160, vcc, 0, v160, s[34:35]
	v_cmp_le_u32_e64 s[50:51], s30, v87
	v_addc_co_u32_e64 v161, vcc, 0, v161, s[36:37]
	v_addc_co_u32_e64 v160, vcc, 0, v160, s[48:49]
	v_addc_co_u32_e64 v161, vcc, 0, v161, s[50:51]
	s_cmp_le_u32 s23, 14
	s_cbranch_scc1 .Ltk0_bred
	v_cmp_le_u32_e64 s[34:35], s30, v88
	v_cmp_le_u32_e64 s[36:37], s30, v89
	v_cmp_le_u32_e64 s[48:49], s30, v90
	v_addc_co_u32_e64 v160, vcc, 0, v160, s[34:35]
	v_cmp_le_u32_e64 s[50:51], s30, v91
	v_addc_co_u32_e64 v161, vcc, 0, v161, s[36:37]
	v_cmp_le_u32_e64 s[34:35], s30, v92
	v_addc_co_u32_e64 v160, vcc, 0, v160, s[48:49]
	v_cmp_le_u32_e64 s[36:37], s30, v93
	v_addc_co_u32_e64 v161, vcc, 0, v161, s[50:51]
	v_cmp_le_u32_e64 s[48:49], s30, v94
	v_addc_co_u32_e64 v160, vcc, 0, v160, s[34:35]
	v_cmp_le_u32_e64 s[50:51], s30, v95
	v_addc_co_u32_e64 v161, vcc, 0, v161, s[36:37]
	v_addc_co_u32_e64 v160, vcc, 0, v160, s[48:49]
	v_addc_co_u32_e64 v161, vcc, 0, v161, s[50:51]
	s_cmp_le_u32 s23, 16
	s_cbranch_scc1 .Ltk0_bred
	v_cmp_le_u32_e64 s[34:35], s30, v96
	v_cmp_le_u32_e64 s[36:37], s30, v97
	v_cmp_le_u32_e64 s[48:49], s30, v98
	v_addc_co_u32_e64 v160, vcc, 0, v160, s[34:35]
	v_cmp_le_u32_e64 s[50:51], s30, v99
	v_addc_co_u32_e64 v161, vcc, 0, v161, s[36:37]
	v_cmp_le_u32_e64 s[34:35], s30, v100
	v_addc_co_u32_e64 v160, vcc, 0, v160, s[48:49]
	v_cmp_le_u32_e64 s[36:37], s30, v101
	v_addc_co_u32_e64 v161, vcc, 0, v161, s[50:51]
	v_cmp_le_u32_e64 s[48:49], s30, v102
	v_addc_co_u32_e64 v160, vcc, 0, v160, s[34:35]
	v_cmp_le_u32_e64 s[50:51], s30, v103
	v_addc_co_u32_e64 v161, vcc, 0, v161, s[36:37]
	v_addc_co_u32_e64 v160, vcc, 0, v160, s[48:49]
	v_addc_co_u32_e64 v161, vcc, 0, v161, s[50:51]
	s_cmp_le_u32 s23, 18
	s_cbranch_scc1 .Ltk0_bred
	v_cmp_le_u32_e64 s[34:35], s30, v104
	v_cmp_le_u32_e64 s[36:37], s30, v105
	v_cmp_le_u32_e64 s[48:49], s30, v106
	v_addc_co_u32_e64 v160, vcc, 0, v160, s[34:35]
	v_cmp_le_u32_e64 s[50:51], s30, v107
	v_addc_co_u32_e64 v161, vcc, 0, v161, s[36:37]
	v_cmp_le_u32_e64 s[34:35], s30, v108
	v_addc_co_u32_e64 v160, vcc, 0, v160, s[48:49]
	v_cmp_le_u32_e64 s[36:37], s30, v109
	v_addc_co_u32_e64 v161, vcc, 0, v161, s[50:51]
	v_cmp_le_u32_e64 s[48:49], s30, v110
	v_addc_co_u32_e64 v160, vcc, 0, v160, s[34:35]
	v_cmp_le_u32_e64 s[50:51], s30, v111
	v_addc_co_u32_e64 v161, vcc, 0, v161, s[36:37]
	v_addc_co_u32_e64 v160, vcc, 0, v160, s[48:49]
	v_addc_co_u32_e64 v161, vcc, 0, v161, s[50:51]
	s_cmp_le_u32 s23, 20
	s_cbranch_scc1 .Ltk0_bred
	v_cmp_le_u32_e64 s[34:35], s30, v112
	v_cmp_le_u32_e64 s[36:37], s30, v113
	v_cmp_le_u32_e64 s[48:49], s30, v114
	v_addc_co_u32_e64 v160, vcc, 0, v160, s[34:35]
	v_cmp_le_u32_e64 s[50:51], s30, v115
	v_addc_co_u32_e64 v161, vcc, 0, v161, s[36:37]
	v_cmp_le_u32_e64 s[34:35], s30, v116
	v_addc_co_u32_e64 v160, vcc, 0, v160, s[48:49]
	v_cmp_le_u32_e64 s[36:37], s30, v117
	v_addc_co_u32_e64 v161, vcc, 0, v161, s[50:51]
	v_cmp_le_u32_e64 s[48:49], s30, v118
	v_addc_co_u32_e64 v160, vcc, 0, v160, s[34:35]
	v_cmp_le_u32_e64 s[50:51], s30, v119
	v_addc_co_u32_e64 v161, vcc, 0, v161, s[36:37]
	v_addc_co_u32_e64 v160, vcc, 0, v160, s[48:49]
	v_addc_co_u32_e64 v161, vcc, 0, v161, s[50:51]
	s_cmp_le_u32 s23, 22
	s_cbranch_scc1 .Ltk0_bred
	v_cmp_le_u32_e64 s[34:35], s30, v120
	v_cmp_le_u32_e64 s[36:37], s30, v121
	v_cmp_le_u32_e64 s[48:49], s30, v122
	v_addc_co_u32_e64 v160, vcc, 0, v160, s[34:35]
	v_cmp_le_u32_e64 s[50:51], s30, v123
	v_addc_co_u32_e64 v161, vcc, 0, v161, s[36:37]
	v_cmp_le_u32_e64 s[34:35], s30, v124
	v_addc_co_u32_e64 v160, vcc, 0, v160, s[48:49]
	v_cmp_le_u32_e64 s[36:37], s30, v125
	v_addc_co_u32_e64 v161, vcc, 0, v161, s[50:51]
	v_cmp_le_u32_e64 s[48:49], s30, v126
	v_addc_co_u32_e64 v160, vcc, 0, v160, s[34:35]
	v_cmp_le_u32_e64 s[50:51], s30, v127
	v_addc_co_u32_e64 v161, vcc, 0, v161, s[36:37]
	v_addc_co_u32_e64 v160, vcc, 0, v160, s[48:49]
	v_addc_co_u32_e64 v161, vcc, 0, v161, s[50:51]
	s_cmp_le_u32 s23, 24
	s_cbranch_scc1 .Ltk0_bred
	v_cmp_le_u32_e64 s[34:35], s30, v128
	v_cmp_le_u32_e64 s[36:37], s30, v129
	v_cmp_le_u32_e64 s[48:49], s30, v130
	v_addc_co_u32_e64 v160, vcc, 0, v160, s[34:35]
	v_cmp_le_u32_e64 s[50:51], s30, v131
	v_addc_co_u32_e64 v161, vcc, 0, v161, s[36:37]
	v_cmp_le_u32_e64 s[34:35], s30, v132
	v_addc_co_u32_e64 v160, vcc, 0, v160, s[48:49]
	v_cmp_le_u32_e64 s[36:37], s30, v133
	v_addc_co_u32_e64 v161, vcc, 0, v161, s[50:51]
	v_cmp_le_u32_e64 s[48:49], s30, v134
	v_addc_co_u32_e64 v160, vcc, 0, v160, s[34:35]
	v_cmp_le_u32_e64 s[50:51], s30, v135
	v_addc_co_u32_e64 v161, vcc, 0, v161, s[36:37]
	v_addc_co_u32_e64 v160, vcc, 0, v160, s[48:49]
	v_addc_co_u32_e64 v161, vcc, 0, v161, s[50:51]
	s_cmp_le_u32 s23, 26
	s_cbranch_scc1 .Ltk0_bred
	v_cmp_le_u32_e64 s[34:35], s30, v136
	v_cmp_le_u32_e64 s[36:37], s30, v137
	v_cmp_le_u32_e64 s[48:49], s30, v138
	v_addc_co_u32_e64 v160, vcc, 0, v160, s[34:35]
	v_cmp_le_u32_e64 s[50:51], s30, v139
	v_addc_co_u32_e64 v161, vcc, 0, v161, s[36:37]
	v_cmp_le_u32_e64 s[34:35], s30, v140
	v_addc_co_u32_e64 v160, vcc, 0, v160, s[48:49]
	v_cmp_le_u32_e64 s[36:37], s30, v141
	v_addc_co_u32_e64 v161, vcc, 0, v161, s[50:51]
	v_cmp_le_u32_e64 s[48:49], s30, v142
	v_addc_co_u32_e64 v160, vcc, 0, v160, s[34:35]
	v_cmp_le_u32_e64 s[50:51], s30, v143
	v_addc_co_u32_e64 v161, vcc, 0, v161, s[36:37]
	v_addc_co_u32_e64 v160, vcc, 0, v160, s[48:49]
	v_addc_co_u32_e64 v161, vcc, 0, v161, s[50:51]
	s_cmp_le_u32 s23, 28
	s_cbranch_scc1 .Ltk0_bred
	v_cmp_le_u32_e64 s[34:35], s30, v144
	v_cmp_le_u32_e64 s[36:37], s30, v145
	v_cmp_le_u32_e64 s[48:49], s30, v146
	v_addc_co_u32_e64 v160, vcc, 0, v160, s[34:35]
	v_cmp_le_u32_e64 s[50:51], s30, v147
	v_addc_co_u32_e64 v161, vcc, 0, v161, s[36:37]
	v_cmp_le_u32_e64 s[34:35], s30, v148
	v_addc_co_u32_e64 v160, vcc, 0, v160, s[48:49]
	v_cmp_le_u32_e64 s[36:37], s30, v149
	v_addc_co_u32_e64 v161, vcc, 0, v161, s[50:51]
	v_cmp_le_u32_e64 s[48:49], s30, v150
	v_addc_co_u32_e64 v160, vcc, 0, v160, s[34:35]
	v_cmp_le_u32_e64 s[50:51], s30, v151
	v_addc_co_u32_e64 v161, vcc, 0, v161, s[36:37]
	v_addc_co_u32_e64 v160, vcc, 0, v160, s[48:49]
	v_addc_co_u32_e64 v161, vcc, 0, v161, s[50:51]
	s_cmp_le_u32 s23, 30
	s_cbranch_scc1 .Ltk0_bred
	v_cmp_le_u32_e64 s[34:35], s30, v152
	v_cmp_le_u32_e64 s[36:37], s30, v153
	v_cmp_le_u32_e64 s[48:49], s30, v154
	v_addc_co_u32_e64 v160, vcc, 0, v160, s[34:35]
	v_cmp_le_u32_e64 s[50:51], s30, v155
	v_addc_co_u32_e64 v161, vcc, 0, v161, s[36:37]
	v_cmp_le_u32_e64 s[34:35], s30, v156
	v_addc_co_u32_e64 v160, vcc, 0, v160, s[48:49]
	v_cmp_le_u32_e64 s[36:37], s30, v157
	v_addc_co_u32_e64 v161, vcc, 0, v161, s[50:51]
	v_cmp_le_u32_e64 s[48:49], s30, v158
	v_addc_co_u32_e64 v160, vcc, 0, v160, s[34:35]
	v_cmp_le_u32_e64 s[50:51], s30, v159
	v_addc_co_u32_e64 v161, vcc, 0, v161, s[36:37]
	v_addc_co_u32_e64 v160, vcc, 0, v160, s[48:49]
	v_addc_co_u32_e64 v161, vcc, 0, v161, s[50:51]
